# C7: +attention Q-load waits deferred, reto prefetch drains removed, ctx_gemm K-loop double-buffered, max-tree canonicalize folded
# speedup vs baseline: 1.0261x; 1.0044x over previous
.LBB0_30:
	v_readlane_b32 s10, v253, 17
	s_cmp_lt_i32 s10, s15
	s_cselect_b64 s[22:23], -1, 0
	s_cmp_ge_i32 s10, s15
	v_readlane_b32 s40, v253, 8
	s_cbranch_scc1 .LBB0_32
	v_readlane_b32 s10, v253, 3
	v_mov_b64_e32 v[2:3], s[72:73]
	v_add_u32_e32 v0, s10, v166
	v_mad_i64_i32 v[2:3], s[10:11], v0, s64, v[2:3]
	v_readlane_b32 s10, v254, 44
	v_readlane_b32 s11, v254, 45
	s_mov_b32 s11, s17
	v_lshlrev_b32_e32 v0, 1, v165
	v_lshl_add_u64 v[2:3], v[2:3], 0, s[10:11]
	v_lshl_add_u64 v[14:15], v[2:3], 0, v[0:1]
	global_load_dwordx4 v[2:5], v[14:15], off offset:528
	global_load_dwordx4 v[6:9], v[14:15], off offset:512
	global_load_dwordx4 v[10:13], v[14:15], off offset:1040
	s_nop 0
	global_load_dwordx4 v[14:17], v[14:15], off offset:1024
	s_mov_b32 s20, s10
	v_writelane_b32 v254, s20, 44
	s_nop 1
	v_writelane_b32 v254, s21, 45
.LBB0_32:
	v_readlane_b32 s20, v253, 23
	s_cmp_lt_i32 s20, s15
	s_cselect_b64 s[10:11], -1, 0
	s_cmp_ge_i32 s20, s15
	s_cbranch_scc1 .LBB0_34
	v_readlane_b32 s20, v253, 4
	v_mov_b64_e32 v[34:35], s[72:73]
	v_add_u32_e32 v0, s20, v166
	v_mad_i64_i32 v[34:35], s[20:21], v0, s64, v[34:35]
	v_readlane_b32 s20, v254, 46
	v_readlane_b32 s21, v254, 47
	s_mov_b32 s21, s17
	v_lshlrev_b32_e32 v0, 1, v165
	v_lshl_add_u64 v[34:35], v[34:35], 0, s[20:21]
	v_lshl_add_u64 v[42:43], v[34:35], 0, v[0:1]
	global_load_dwordx4 v[38:41], v[42:43], off offset:528
	global_load_dwordx4 v[46:49], v[42:43], off offset:512
	global_load_dwordx4 v[34:37], v[42:43], off offset:1040
	s_nop 0
	global_load_dwordx4 v[42:45], v[42:43], off offset:1024
	s_waitcnt lgkmcnt(0)
	s_mov_b32 s28, s20
	v_writelane_b32 v254, s28, 46
	s_nop 1
	v_writelane_b32 v254, s29, 47

.LBB0_101:
	v_readfirstlane_b32 s2, v140
	s_ashr_i32 s3, s2, 7
	s_and_b32 s22, s58, 1
	s_lshr_b32 s2, s2, 1
	s_lshl_b32 s10, s22, 6
	s_and_b32 s2, s2, 32
	s_or_b32 s26, s2, s10
	s_ashr_i32 s2, s58, 2
	s_bfe_u32 s28, s58, 0x10001
	s_lshl_b32 s10, s28, 2
	s_lshl_b32 s29, s2, 7
	s_add_i32 s74, s3, s10
	v_or_b32_e32 v0, s29, v145
	v_or_b32_e32 v152, s26, v0
	s_lshl_b32 s10, s74, 6
	s_ashr_i32 s11, s10, 31
	v_mov_b64_e32 v[2:3], s[72:73]
	v_or_b32_e32 v150, 16, v152
	v_mad_i64_i32 v[4:5], s[20:21], v152, s64, v[2:3]
	s_lshl_b64 s[82:83], s[10:11], 1
	v_mad_i64_i32 v[2:3], s[10:11], v150, s64, v[2:3]
	v_lshl_add_u64 v[4:5], v[4:5], 0, s[82:83]
	v_lshlrev_b32_e32 v0, 1, v146
	v_lshl_add_u64 v[2:3], v[2:3], 0, s[82:83]
	s_waitcnt vmcnt(2)
	v_lshl_add_u64 v[6:7], v[4:5], 0, v[0:1]
	s_waitcnt vmcnt(0)
	v_lshl_add_u64 v[14:15], v[2:3], 0, v[0:1]
	global_load_dwordx4 v[2:5], v[6:7], off offset:2048
	s_nop 0
	global_load_dwordx4 v[6:9], v[6:7], off offset:2112
	s_nop 0
	global_load_dwordx4 v[10:13], v[14:15], off offset:2048
	s_nop 0
	global_load_dwordx4 v[14:17], v[14:15], off offset:2112
	s_and_b32 s40, s2, 0x7f
	s_cmp_eq_u32 s40, 0
	s_cselect_b64 s[10:11], -1, 0
	s_add_i32 s3, s2, 0xffffff00
	s_ashr_i32 s16, s58, 9
	s_lshr_b32 s20, s3, 1
	s_cmpk_lt_i32 s2, 0x100
	s_cselect_b64 s[78:79], -1, 0
	v_cndmask_b32_e64 v0, 0, 1, s[10:11]
	s_and_b64 s[2:3], s[78:79], exec
	s_cselect_b32 s2, s16, s20
	v_readfirstlane_b32 s21, v0
	s_cselect_b32 s20, s21, 3
	s_lshl_b32 s23, s2, 8
	s_addk_i32 s23, 0x7e80
	v_ashrrev_i32_e32 v153, 31, v152
	v_ashrrev_i32_e32 v151, 31, v150
	s_cmp_lt_i32 s20, 1
	s_cbranch_scc1 .LBB0_106
	s_cmp_lg_u32 s20, 1
	s_mov_b64 s[2:3], -1
	s_cbranch_scc0 .LBB0_104
	s_lshl_b32 s2, s20, 7
	s_add_i32 s16, s23, s2
	s_mov_b64 s[2:3], 0

.LBB0_126:
	v_max_f32_e32 v163, v110, v111
	v_max_f32_e32 v164, v112, v113
	v_max_f32_e32 v165, v128, v129
	v_max3_f32 v165, v126, v127, v165
	v_max3_f32 v163, v163, v164, v165
	v_max_f32_e32 v164, v132, v133
	v_max_f32_e32 v165, v136, v137
	v_max3_f32 v164, v130, v131, v164
	v_max3_f32 v165, v134, v135, v165
	v_max3_f32 v211, v163, v164, v165
	v_max_f32_e32 v163, v114, v115
	v_max_f32_e32 v164, v116, v117
	v_max_f32_e32 v165, v120, v121
	v_max3_f32 v165, v118, v119, v165
	v_max3_f32 v163, v163, v164, v165
	v_max_f32_e32 v164, v124, v125
	v_max_f32_e32 v165, v108, v109
	s_xor_b64 s[28:29], s[94:95], -1
	v_max3_f32 v164, v122, v123, v164
	v_max3_f32 v165, v106, v107, v165
	v_cndmask_b32_e64 v166, 0, 1, s[28:29]
	v_cmp_ne_u32_e64 s[40:41], 1, v166
	s_andn2_b64 vcc, exec, s[28:29]
	v_max3_f32 v212, v163, v164, v165
	s_cbranch_vccnz .LBB0_128
	v_max_f32_e32 v163, v211, v211
	v_max_f32_e32 v164, v212, v212
	v_max_f32_e32 v163, v164, v163
	v_cmp_lt_f32_e32 vcc, s30, v163
	s_mov_b64 s[94:95], -1
	s_cbranch_vccz .LBB0_145
.LBB0_128:
	s_and_b64 vcc, exec, s[94:95]
	s_cbranch_vccz .LBB0_121
	v_mov_b32_e32 v163, v211
	s_nop 1
	v_permlane16_swap_b32_e32 v211, v163
	v_max_f32_e32 v163, v211, v163
	v_mov_b32_e32 v164, v163
	s_nop 1
	v_permlane32_swap_b32_e32 v163, v164
	v_max_f32_e32 v164, v164, v164
	v_max_f32_e32 v163, v163, v163
	v_max_f32_e32 v165, v163, v164
	v_mov_b32_e32 v163, v212
	s_nop 1
	v_permlane16_swap_b32_e32 v212, v163
	v_max_f32_e32 v163, v212, v163
	v_mov_b32_e32 v164, v163
	s_nop 1
	v_permlane32_swap_b32_e32 v163, v164
	s_mov_b64 s[42:43], -1
	s_and_b64 vcc, exec, s[28:29]
	s_cbranch_vccz .LBB0_140
	v_cmp_lt_f32_e32 vcc, s30, v165
	v_mov_b32_e32 v211, 0
	s_and_saveexec_b64 s[28:29], vcc
	v_mov_b32_e32 v211, v165
	s_or_b64 exec, exec, s[28:29]
	s_cbranch_execz .LBB0_141

.LBB0_155:
	v_max_f32_e32 v0, v110, v111
	v_max_f32_e32 v162, v112, v113
	v_max_f32_e32 v163, v128, v129
	v_max3_f32 v163, v126, v127, v163
	v_max3_f32 v0, v0, v162, v163
	v_max_f32_e32 v162, v132, v133
	v_max_f32_e32 v163, v136, v137
	v_max3_f32 v162, v130, v131, v162
	v_max3_f32 v163, v134, v135, v163
	v_max3_f32 v209, v0, v162, v163
	v_max_f32_e32 v0, v114, v115
	v_max_f32_e32 v162, v116, v117
	v_max_f32_e32 v163, v120, v121
	v_max3_f32 v163, v118, v119, v163
	v_max3_f32 v0, v0, v162, v163
	v_max_f32_e32 v162, v124, v125
	v_max_f32_e32 v163, v108, v109
	s_xor_b64 s[20:21], s[94:95], -1
	v_max3_f32 v162, v122, v123, v162
	v_max3_f32 v163, v106, v107, v163
	v_cndmask_b32_e64 v164, 0, 1, s[20:21]
	v_cmp_ne_u32_e64 s[40:41], 1, v164
	s_andn2_b64 vcc, exec, s[20:21]
	v_max3_f32 v210, v0, v162, v163
	s_cbranch_vccnz .LBB0_157
	v_max_f32_e32 v0, v209, v209
	v_max_f32_e32 v162, v210, v210
	v_max_f32_e32 v0, v162, v0
	v_cmp_lt_f32_e32 vcc, s30, v0
	s_mov_b64 s[94:95], -1
	s_cbranch_vccz .LBB0_174
.LBB0_157:
	s_and_b64 vcc, exec, s[94:95]
	s_cbranch_vccz .LBB0_150
	v_mov_b32_e32 v0, v209
	s_nop 1
	v_permlane16_swap_b32_e32 v209, v0
	v_max_f32_e32 v0, v209, v0
	v_mov_b32_e32 v162, v0
	s_nop 1
	v_permlane32_swap_b32_e32 v0, v162
	v_max_f32_e32 v162, v162, v162
	v_max_f32_e32 v0, v0, v0
	v_max_f32_e32 v163, v0, v162
	v_mov_b32_e32 v0, v210
	s_nop 1
	v_permlane16_swap_b32_e32 v210, v0
	v_max_f32_e32 v0, v210, v0
	v_mov_b32_e32 v162, v0
	s_nop 1
	v_permlane32_swap_b32_e32 v0, v162
	s_and_b64 vcc, exec, s[40:41]
	s_mov_b64 s[42:43], -1
	s_cbranch_vccnz .LBB0_169
	v_cmp_lt_f32_e32 vcc, s30, v163
	v_mov_b32_e32 v209, 0
	s_and_saveexec_b64 s[42:43], vcc
	v_mov_b32_e32 v209, v163
	s_or_b64 exec, exec, s[42:43]
	s_cbranch_execz .LBB0_170

.LBB0_183:
	v_max_f32_e32 v0, v94, v95
	v_max_f32_e32 v122, v96, v97
	v_max_f32_e32 v123, v112, v113
	v_max3_f32 v123, v110, v111, v123
	v_max3_f32 v0, v0, v122, v123
	v_max_f32_e32 v122, v116, v117
	v_max_f32_e32 v123, v120, v121
	v_max3_f32 v122, v114, v115, v122
	v_max3_f32 v123, v118, v119, v123
	v_max3_f32 v193, v0, v122, v123
	v_max_f32_e32 v0, v98, v99
	v_max_f32_e32 v122, v100, v101
	v_max_f32_e32 v123, v104, v105
	v_max3_f32 v123, v102, v103, v123
	v_max3_f32 v0, v0, v122, v123
	v_max_f32_e32 v122, v108, v109
	v_max_f32_e32 v123, v92, v93
	s_xor_b64 s[20:21], s[94:95], -1
	v_max3_f32 v122, v106, v107, v122
	v_max3_f32 v123, v90, v91, v123
	v_cndmask_b32_e64 v124, 0, 1, s[20:21]
	v_cmp_ne_u32_e64 s[40:41], 1, v124
	s_andn2_b64 vcc, exec, s[20:21]
	v_max3_f32 v194, v0, v122, v123
	s_cbranch_vccnz .LBB0_185
	v_max_f32_e32 v0, v193, v193
	v_max_f32_e32 v122, v194, v194
	v_max_f32_e32 v0, v122, v0
	v_cmp_lt_f32_e32 vcc, s30, v0
	s_mov_b64 s[94:95], -1
	s_cbranch_vccz .LBB0_202
.LBB0_185:
	s_and_b64 vcc, exec, s[94:95]
	s_cbranch_vccz .LBB0_178
	v_mov_b32_e32 v0, v193
	s_nop 1
	v_permlane16_swap_b32_e32 v193, v0
	v_max_f32_e32 v0, v193, v0
	v_mov_b32_e32 v122, v0
	s_nop 1
	v_permlane32_swap_b32_e32 v0, v122
	v_max_f32_e32 v122, v122, v122
	v_max_f32_e32 v0, v0, v0
	v_max_f32_e32 v123, v0, v122
	v_mov_b32_e32 v0, v194
	s_nop 1
	v_permlane16_swap_b32_e32 v194, v0
	v_max_f32_e32 v0, v194, v0
	v_mov_b32_e32 v122, v0
	s_nop 1
	v_permlane32_swap_b32_e32 v0, v122
	s_and_b64 vcc, exec, s[40:41]
	s_mov_b64 s[26:27], -1
	s_cbranch_vccnz .LBB0_197
	v_cmp_lt_f32_e32 vcc, s30, v123
	v_mov_b32_e32 v193, 0
	s_and_saveexec_b64 s[26:27], vcc
	v_mov_b32_e32 v193, v123
	s_or_b64 exec, exec, s[26:27]
	s_cbranch_execz .LBB0_198

.LBB0_205:
	v_or_b32_e32 v0, s16, v145
	v_mad_u32_u24 v0, v0, s65, v158
	ds_read_b128 v[74:77], v0 offset:36864
	ds_read_b128 v[82:85], v0 offset:36928
	v_xor_b32_e32 v102, 0x80000000, v149
	v_xor_b32_e32 v106, 0x80000000, v159
	v_mov_b32_e32 v103, v102
	v_mov_b32_e32 v104, v102
	v_mov_b32_e32 v105, v102
	v_mov_b32_e32 v107, v106
	v_mov_b32_e32 v108, v106
	v_mov_b32_e32 v109, v106
	s_waitcnt lgkmcnt(1)
	v_mfma_f32_16x16x32_bf16 v[78:81], v[74:77], v[2:5], v[102:105]
	s_and_b64 vcc, exec, s[94:95]
	s_mov_b64 s[10:11], s[94:95]
	v_mfma_f32_16x16x32_bf16 v[74:77], v[74:77], v[10:13], v[106:109]
	s_waitcnt lgkmcnt(0)
	v_mfma_f32_16x16x32_bf16 v[78:81], v[82:85], v[6:9], v[78:81]
	v_mfma_f32_16x16x32_bf16 v[82:85], v[82:85], v[14:17], v[74:77]
	s_nop 4
	ds_read_b128 v[74:77], v0 offset:39168
	ds_read_b128 v[86:89], v0 offset:39232
	s_waitcnt lgkmcnt(1)
	v_mfma_f32_16x16x32_bf16 v[90:93], v[74:77], v[2:5], v[102:105]
	v_mfma_f32_16x16x32_bf16 v[74:77], v[74:77], v[10:13], v[106:109]
	s_waitcnt lgkmcnt(0)
	v_mfma_f32_16x16x32_bf16 v[94:97], v[86:89], v[6:9], v[90:93]
	v_mfma_f32_16x16x32_bf16 v[86:89], v[86:89], v[14:17], v[74:77]
	s_nop 4
	ds_read_b128 v[74:77], v0 offset:41472
	ds_read_b128 v[90:93], v0 offset:41536
	s_waitcnt lgkmcnt(1)
	v_mfma_f32_16x16x32_bf16 v[98:101], v[74:77], v[2:5], v[102:105]
	v_mfma_f32_16x16x32_bf16 v[74:77], v[74:77], v[10:13], v[106:109]
	s_waitcnt lgkmcnt(0)
	v_mfma_f32_16x16x32_bf16 v[98:101], v[90:93], v[6:9], v[98:101]
	v_mfma_f32_16x16x32_bf16 v[90:93], v[90:93], v[14:17], v[74:77]
	s_nop 4
	ds_read_b128 v[74:77], v0 offset:43776
	ds_read_b128 v[110:113], v0 offset:43840
	v_max_f32_e32 v0, v79, v79
	s_waitcnt lgkmcnt(1)
	v_mfma_f32_16x16x32_bf16 v[102:105], v[74:77], v[2:5], v[102:105]
	v_mfma_f32_16x16x32_bf16 v[74:77], v[74:77], v[10:13], v[106:109]
	s_waitcnt lgkmcnt(0)
	v_mfma_f32_16x16x32_bf16 v[102:105], v[110:113], v[6:9], v[102:105]
	s_nop 0
	v_max_f32_e32 v106, v78, v78
	v_max_f32_e32 v0, v106, v0
	v_max_f32_e32 v106, v80, v81
	v_max_f32_e32 v107, v96, v97
	v_max3_f32 v107, v94, v95, v107
	v_max3_f32 v0, v0, v106, v107
	v_max_f32_e32 v106, v100, v101
	v_max_f32_e32 v107, v104, v105
	v_max3_f32 v106, v98, v99, v106
	v_max3_f32 v107, v102, v103, v107
	v_max3_f32 v136, v0, v106, v107
	v_max_f32_e32 v0, v82, v83
	v_max_f32_e32 v106, v85, v85
	v_max_f32_e32 v107, v84, v84
	v_mfma_f32_16x16x32_bf16 v[74:77], v[110:113], v[14:17], v[74:77]
	v_max_f32_e32 v106, v107, v106
	v_max_f32_e32 v107, v88, v89
	v_max3_f32 v107, v86, v87, v107
	v_max3_f32 v0, v0, v106, v107
	v_max_f32_e32 v106, v92, v93
	s_nop 2
	v_max_f32_e32 v107, v77, v77
	v_max_f32_e32 v108, v76, v76
	v_max_f32_e32 v107, v108, v107
	v_max3_f32 v106, v90, v91, v106
	v_max3_f32 v107, v74, v75, v107
	v_max3_f32 v137, v0, v106, v107
	s_cbranch_vccnz .LBB0_207
	v_max_f32_e32 v0, v137, v137
	v_max_f32_e32 v106, v136, v136
	v_max_f32_e32 v0, v106, v0
	v_cmp_lt_f32_e32 vcc, s30, v0
	s_mov_b64 s[10:11], -1
	s_cbranch_vccz .LBB0_227
.LBB0_207:
	s_and_b64 vcc, exec, s[10:11]
	s_cbranch_vccz .LBB0_221
	v_mov_b32_e32 v0, v136
	s_nop 1
	v_permlane16_swap_b32_e32 v136, v0
	v_max_f32_e32 v0, v136, v0
	v_mov_b32_e32 v106, v0
	s_nop 1
	v_permlane32_swap_b32_e32 v0, v106
	v_max_f32_e32 v106, v106, v106
	v_max_f32_e32 v0, v0, v0
	v_max_f32_e32 v107, v0, v106
	v_mov_b32_e32 v0, v137
	s_nop 1
	v_permlane16_swap_b32_e32 v137, v0
	v_max_f32_e32 v0, v137, v0
	s_xor_b64 s[10:11], s[94:95], -1
	v_mov_b32_e32 v106, v0
	v_cndmask_b32_e64 v108, 0, 1, s[10:11]
	s_nop 0
	v_permlane32_swap_b32_e32 v0, v106
	v_cmp_ne_u32_e64 s[40:41], 1, v108
	s_andn2_b64 vcc, exec, s[10:11]
	s_mov_b64 s[10:11], -1
	s_cbranch_vccnz .LBB0_223
	v_cmp_lt_f32_e32 vcc, s30, v107
	v_mov_b32_e32 v136, 0
	s_and_saveexec_b64 s[10:11], vcc
	v_mov_b32_e32 v136, v107
	s_or_b64 exec, exec, s[10:11]
	s_cbranch_execz .LBB0_224

.LBB0_230:
	v_or_b32_e32 v0, s16, v145
	v_mad_u32_u24 v0, v0, s65, v158
	ds_read_b128 v[58:61], v0
	ds_read_b128 v[66:69], v0 offset:64
	v_xor_b32_e32 v86, 0x80000000, v149
	v_xor_b32_e32 v90, 0x80000000, v159
	v_mov_b32_e32 v87, v86
	v_mov_b32_e32 v88, v86
	v_mov_b32_e32 v89, v86
	v_mov_b32_e32 v91, v90
	v_mov_b32_e32 v92, v90
	v_mov_b32_e32 v93, v90
	s_waitcnt lgkmcnt(1)
	v_mfma_f32_16x16x32_bf16 v[62:65], v[58:61], v[2:5], v[86:89]
	s_and_b64 vcc, exec, s[94:95]
	s_mov_b64 s[10:11], s[94:95]
	v_mfma_f32_16x16x32_bf16 v[58:61], v[58:61], v[10:13], v[90:93]
	s_waitcnt lgkmcnt(0)
	v_mfma_f32_16x16x32_bf16 v[62:65], v[66:69], v[6:9], v[62:65]
	v_mfma_f32_16x16x32_bf16 v[66:69], v[66:69], v[14:17], v[58:61]
	s_nop 4
	ds_read_b128 v[58:61], v0 offset:2304
	ds_read_b128 v[70:73], v0 offset:2368
	s_waitcnt lgkmcnt(1)
	v_mfma_f32_16x16x32_bf16 v[74:77], v[58:61], v[2:5], v[86:89]
	v_mfma_f32_16x16x32_bf16 v[58:61], v[58:61], v[10:13], v[90:93]
	s_waitcnt lgkmcnt(0)
	v_mfma_f32_16x16x32_bf16 v[78:81], v[70:73], v[6:9], v[74:77]
	v_mfma_f32_16x16x32_bf16 v[70:73], v[70:73], v[14:17], v[58:61]
	s_nop 4
	ds_read_b128 v[58:61], v0 offset:4608
	ds_read_b128 v[74:77], v0 offset:4672
	s_waitcnt lgkmcnt(1)
	v_mfma_f32_16x16x32_bf16 v[82:85], v[58:61], v[2:5], v[86:89]
	v_mfma_f32_16x16x32_bf16 v[58:61], v[58:61], v[10:13], v[90:93]
	s_waitcnt lgkmcnt(0)
	v_mfma_f32_16x16x32_bf16 v[82:85], v[74:77], v[6:9], v[82:85]
	v_mfma_f32_16x16x32_bf16 v[74:77], v[74:77], v[14:17], v[58:61]
	s_nop 4
	ds_read_b128 v[58:61], v0 offset:6912
	ds_read_b128 v[94:97], v0 offset:6976
	v_max_f32_e32 v0, v63, v63
	s_waitcnt lgkmcnt(1)
	v_mfma_f32_16x16x32_bf16 v[86:89], v[58:61], v[2:5], v[86:89]
	v_mfma_f32_16x16x32_bf16 v[58:61], v[58:61], v[10:13], v[90:93]
	s_waitcnt lgkmcnt(0)
	v_mfma_f32_16x16x32_bf16 v[86:89], v[94:97], v[6:9], v[86:89]
	s_nop 0
	v_max_f32_e32 v90, v62, v62
	v_max_f32_e32 v0, v90, v0
	v_max_f32_e32 v90, v64, v65
	v_max_f32_e32 v91, v80, v81
	v_max3_f32 v91, v78, v79, v91
	v_max3_f32 v0, v0, v90, v91
	v_max_f32_e32 v90, v84, v85
	v_max_f32_e32 v91, v88, v89
	v_max3_f32 v90, v82, v83, v90
	v_max3_f32 v91, v86, v87, v91
	v_max3_f32 v120, v0, v90, v91
	v_max_f32_e32 v0, v66, v67
	v_max_f32_e32 v90, v69, v69
	v_max_f32_e32 v91, v68, v68
	v_mfma_f32_16x16x32_bf16 v[58:61], v[94:97], v[14:17], v[58:61]
	v_max_f32_e32 v90, v91, v90
	v_max_f32_e32 v91, v72, v73
	v_max3_f32 v91, v70, v71, v91
	v_max3_f32 v0, v0, v90, v91
	v_max_f32_e32 v90, v76, v77
	s_nop 2
	v_max_f32_e32 v91, v61, v61
	v_max_f32_e32 v92, v60, v60
	v_max_f32_e32 v91, v92, v91
	v_max3_f32 v90, v74, v75, v90
	v_max3_f32 v91, v58, v59, v91
	v_max3_f32 v121, v0, v90, v91
	s_cbranch_vccnz .LBB0_232
	v_max_f32_e32 v0, v121, v121
	v_max_f32_e32 v90, v120, v120
	v_max_f32_e32 v0, v90, v0
	v_cmp_lt_f32_e32 vcc, s30, v0
	s_mov_b64 s[10:11], -1
	s_cbranch_vccz .LBB0_252
.LBB0_232:
	s_and_b64 vcc, exec, s[10:11]
	s_cbranch_vccz .LBB0_246
	v_mov_b32_e32 v0, v120
	s_nop 1
	v_permlane16_swap_b32_e32 v120, v0
	v_max_f32_e32 v0, v120, v0
	v_mov_b32_e32 v90, v0
	s_nop 1
	v_permlane32_swap_b32_e32 v0, v90
	v_max_f32_e32 v90, v90, v90
	v_max_f32_e32 v0, v0, v0
	v_max_f32_e32 v91, v0, v90
	v_mov_b32_e32 v0, v121
	s_nop 1
	v_permlane16_swap_b32_e32 v121, v0
	v_max_f32_e32 v0, v121, v0
	s_xor_b64 s[10:11], s[94:95], -1
	v_mov_b32_e32 v90, v0
	v_cndmask_b32_e64 v92, 0, 1, s[10:11]
	s_nop 0
	v_permlane32_swap_b32_e32 v0, v90
	v_cmp_ne_u32_e64 s[40:41], 1, v92
	s_andn2_b64 vcc, exec, s[10:11]
	s_mov_b64 s[10:11], -1
	s_cbranch_vccnz .LBB0_248
	v_cmp_lt_f32_e32 vcc, s30, v91
	v_mov_b32_e32 v120, 0
	s_and_saveexec_b64 s[10:11], vcc
	v_mov_b32_e32 v120, v91
	s_or_b64 exec, exec, s[10:11]
	s_cbranch_execz .LBB0_249

.LBB0_722:
	s_lshl_b32 s16, s21, 6
	s_and_b32 s28, s16, 0x3c0
	v_or_b32_e32 v0, s28, v52
	s_lshl_b32 s29, s21, 1
	v_mul_u32_u24_e32 v0, s46, v0
	s_andn2_b32 s29, s29, 31
	v_lshlrev_b32_e32 v0, 1, v0
	v_or_b32_e32 v2, s29, v52
	v_lshl_add_u64 v[42:43], v[36:37], 0, v[0:1]
	s_mov_b32 s27, s17
	v_mad_i64_i32 v[2:3], s[40:41], v2, s46, 0
	v_lshl_add_u64 v[44:45], v[42:43], 0, s[26:27]
	v_lshl_add_u64 v[40:41], v[2:3], 1, v[34:35]
	v_lshl_add_u64 v[46:47], v[44:45], 0, s[26:27]
	v_mov_b32_e32 v2, 0
	v_lshl_add_u64 v[48:49], v[46:47], 0, s[26:27]
	v_lshl_add_u64 v[50:51], v[40:41], 0, s[22:23]
	s_mov_b32 s16, 0
	s_mov_b32 s27, s15
	v_mov_b32_e32 v3, v2
	v_mov_b32_e32 v4, v2
	v_mov_b32_e32 v5, v2
	v_mov_b32_e32 v6, v2
	v_mov_b32_e32 v7, v2
	v_mov_b32_e32 v8, v2
	v_mov_b32_e32 v9, v2
	v_mov_b32_e32 v10, v2
	v_mov_b32_e32 v11, v2
	v_mov_b32_e32 v12, v2
	v_mov_b32_e32 v13, v2
	v_mov_b32_e32 v14, v2
	v_mov_b32_e32 v15, v2
	v_mov_b32_e32 v16, v2
	v_mov_b32_e32 v17, v2
	v_mov_b32_e32 v18, v2
	v_mov_b32_e32 v19, v2
	v_mov_b32_e32 v20, v2
	v_mov_b32_e32 v21, v2
	v_mov_b32_e32 v22, v2
	v_mov_b32_e32 v23, v2
	v_mov_b32_e32 v24, v2
	v_mov_b32_e32 v25, v2
	v_mov_b32_e32 v26, v2
	v_mov_b32_e32 v27, v2
	v_mov_b32_e32 v28, v2
	v_mov_b32_e32 v29, v2
	v_mov_b32_e32 v30, v2
	v_mov_b32_e32 v31, v2
	v_mov_b32_e32 v32, v2
	v_mov_b32_e32 v33, v2
	s_mov_b32 s16, 0xffffffe0
	s_add_i32 s16, s16, 32
	s_lshl_b64 s[40:41], s[16:17], 1
	v_lshl_add_u64 v[58:59], v[42:43], 0, s[40:41]
	v_lshl_add_u64 v[62:63], v[40:41], 0, s[40:41]
	v_lshl_add_u64 v[66:67], v[44:45], 0, s[40:41]
	v_lshl_add_u64 v[70:71], v[46:47], 0, s[40:41]
	v_lshl_add_u64 v[74:75], v[48:49], 0, s[40:41]
	v_lshl_add_u64 v[80:81], v[50:51], 0, s[40:41]
	global_load_dwordx4 v[58:61], v[58:59], off
	global_load_dwordx4 v[62:65], v[62:63], off
	global_load_dwordx4 v[66:69], v[66:67], off
	global_load_dwordx4 v[70:73], v[70:71], off
	global_load_dwordx4 v[74:77], v[74:75], off
	global_load_dwordx4 v[80:83], v[80:81], off
.LBB0_723:
	s_add_i32 s16, s16, 32
	s_lshl_b64 s[40:41], s[16:17], 1
	v_lshl_add_u64 v[84:85], v[42:43], 0, s[40:41]
	v_lshl_add_u64 v[88:89], v[40:41], 0, s[40:41]
	v_lshl_add_u64 v[92:93], v[44:45], 0, s[40:41]
	v_lshl_add_u64 v[96:97], v[46:47], 0, s[40:41]
	v_lshl_add_u64 v[100:101], v[48:49], 0, s[40:41]
	v_lshl_add_u64 v[104:105], v[50:51], 0, s[40:41]
	global_load_dwordx4 v[84:87], v[84:85], off
	global_load_dwordx4 v[88:91], v[88:89], off
	global_load_dwordx4 v[92:95], v[92:93], off
	global_load_dwordx4 v[96:99], v[96:97], off
	global_load_dwordx4 v[100:103], v[100:101], off
	global_load_dwordx4 v[104:107], v[104:105], off
	s_add_i32 s27, s27, -1
	s_waitcnt vmcnt(10)
	v_mfma_f32_16x16x32_bf16 v[30:33], v[58:61], v[62:65], v[30:33]
	s_waitcnt vmcnt(9)
	v_mfma_f32_16x16x32_bf16 v[26:29], v[66:69], v[62:65], v[26:29]
	s_waitcnt vmcnt(8)
	v_mfma_f32_16x16x32_bf16 v[22:25], v[70:73], v[62:65], v[22:25]
	s_waitcnt vmcnt(7)
	v_mfma_f32_16x16x32_bf16 v[18:21], v[74:77], v[62:65], v[18:21]
	s_waitcnt vmcnt(6)
	v_mfma_f32_16x16x32_bf16 v[14:17], v[58:61], v[80:83], v[14:17]
	v_mfma_f32_16x16x32_bf16 v[10:13], v[66:69], v[80:83], v[10:13]
	v_mfma_f32_16x16x32_bf16 v[6:9], v[70:73], v[80:83], v[6:9]
	v_mfma_f32_16x16x32_bf16 v[2:5], v[74:77], v[80:83], v[2:5]
	s_cmp_eq_u32 s27, 0
	s_cbranch_scc1 .Lmy_ctx_done
	s_add_i32 s16, s16, 32
	s_lshl_b64 s[40:41], s[16:17], 1
	v_lshl_add_u64 v[58:59], v[42:43], 0, s[40:41]
	v_lshl_add_u64 v[62:63], v[40:41], 0, s[40:41]
	v_lshl_add_u64 v[66:67], v[44:45], 0, s[40:41]
	v_lshl_add_u64 v[70:71], v[46:47], 0, s[40:41]
	v_lshl_add_u64 v[74:75], v[48:49], 0, s[40:41]
	v_lshl_add_u64 v[80:81], v[50:51], 0, s[40:41]
	global_load_dwordx4 v[58:61], v[58:59], off
	global_load_dwordx4 v[62:65], v[62:63], off
	global_load_dwordx4 v[66:69], v[66:67], off
	global_load_dwordx4 v[70:73], v[70:71], off
	global_load_dwordx4 v[74:77], v[74:75], off
	global_load_dwordx4 v[80:83], v[80:81], off
	s_add_i32 s27, s27, -1
	s_waitcnt vmcnt(10)
	v_mfma_f32_16x16x32_bf16 v[30:33], v[84:87], v[88:91], v[30:33]
	s_waitcnt vmcnt(9)
	v_mfma_f32_16x16x32_bf16 v[26:29], v[92:95], v[88:91], v[26:29]
	s_waitcnt vmcnt(8)
	v_mfma_f32_16x16x32_bf16 v[22:25], v[96:99], v[88:91], v[22:25]
	s_waitcnt vmcnt(7)
	v_mfma_f32_16x16x32_bf16 v[18:21], v[100:103], v[88:91], v[18:21]
	s_waitcnt vmcnt(6)
	v_mfma_f32_16x16x32_bf16 v[14:17], v[84:87], v[104:107], v[14:17]
	v_mfma_f32_16x16x32_bf16 v[10:13], v[92:95], v[104:107], v[10:13]
	v_mfma_f32_16x16x32_bf16 v[6:9], v[96:99], v[104:107], v[6:9]
	v_mfma_f32_16x16x32_bf16 v[2:5], v[100:103], v[104:107], v[2:5]
	s_cmp_eq_u32 s27, 0
	s_cbranch_scc0 .LBB0_723
.Lmy_ctx_done:
	v_add_u32_e32 v0, s20, v53
	ds_write_b128 v0, v[30:33]
	ds_write_b128 v0, v[26:29] offset:1024
	ds_write_b128 v0, v[22:25] offset:2048
	ds_write_b128 v0, v[18:21] offset:3072
	ds_write_b128 v0, v[14:17] offset:4096
	ds_write_b128 v0, v[10:13] offset:5120
	ds_write_b128 v0, v[6:9] offset:6144
	ds_write_b128 v0, v[2:5] offset:7168
	s_waitcnt lgkmcnt(0)
	s_barrier
	ds_read_b128 v[2:5], v54
	ds_read_b128 v[6:9], v55 offset:8192
	v_or_b32_e32 v0, s28, v57
	v_lshlrev_b32_e32 v0, 2, v0
	v_mov_b32_e32 v143, v142
	s_add_i32 s21, s21, s96
	s_waitcnt lgkmcnt(0)
	v_pk_add_f32 v[8:9], v[4:5], v[8:9]
	v_pk_add_f32 v[6:7], v[2:3], v[6:7]
	ds_read_b128 v[2:5], v55 offset:16384
	s_cmpk_gt_i32 s21, 0xff
	s_waitcnt lgkmcnt(0)
	v_pk_add_f32 v[8:9], v[8:9], v[4:5]
	v_pk_add_f32 v[6:7], v[6:7], v[2:3]
	ds_read_b128 v[2:5], v55 offset:24576
	s_waitcnt lgkmcnt(0)
	v_pk_add_f32 v[8:9], v[8:9], v[4:5]
	v_pk_add_f32 v[6:7], v[6:7], v[2:3]
	ds_read_b128 v[2:5], v55 offset:32768
	s_waitcnt lgkmcnt(0)
	v_pk_add_f32 v[8:9], v[8:9], v[4:5]
	v_pk_add_f32 v[6:7], v[6:7], v[2:3]
	ds_read_b128 v[2:5], v55 offset:40960
	s_waitcnt lgkmcnt(0)
	v_pk_add_f32 v[8:9], v[8:9], v[4:5]
	v_pk_add_f32 v[6:7], v[6:7], v[2:3]
	ds_read_b128 v[2:5], v55 offset:49152
	s_waitcnt lgkmcnt(0)
	v_pk_add_f32 v[8:9], v[8:9], v[4:5]
	v_pk_add_f32 v[6:7], v[6:7], v[2:3]
	ds_read_b128 v[2:5], v55 offset:57344
	s_waitcnt lgkmcnt(0)
	v_pk_add_f32 v[12:13], v[6:7], v[2:3]
	v_add_u32_e32 v2, s29, v56
	v_ashrrev_i32_e32 v3, 31, v2
	v_lshlrev_b64 v[2:3], 12, v[2:3]
	v_pk_add_f32 v[10:11], v[8:9], v[4:5]
	v_lshl_add_u64 v[4:5], s[48:49], 0, v[2:3]
	v_lshl_add_u64 v[2:3], s[2:3], 0, v[2:3]
	v_lshl_add_u64 v[2:3], v[2:3], 0, v[0:1]
	v_lshl_add_u64 v[14:15], v[4:5], 0, v[0:1]
	global_load_dwordx4 v[2:5], v[2:3], off
	s_nop 0
	global_load_dwordx4 v[6:9], v0, s[10:11]
	s_waitcnt vmcnt(0)
	v_pk_mul_f32 v[6:7], v[12:13], v[6:7]
	v_pk_mul_f32 v[8:9], v[10:11], v[8:9]
	v_pk_fma_f32 v[2:3], v[38:39], v[6:7], v[2:3]
	v_add_co_u32_e32 v6, vcc, 0x8000000, v14
	v_pk_fma_f32 v[4:5], v[142:143], v[8:9], v[4:5]
	s_nop 0
	v_addc_co_u32_e32 v7, vcc, 0, v15, vcc
	global_store_dwordx4 v[6:7], v[2:5], off
	s_barrier
	s_cbranch_scc0 .LBB0_722
